# speedup vs baseline: 1.0107x; 1.0107x over previous
; #define PG8_BAR __builtin_amdgcn_s_barrier()
; template <class Epi, class Sched, bool ALIGN_EPI = false, bool SP2 = false>
; __device__ __forceinline__ void gemm_phase(PG8_LAS unsigned char* lds, const Gemm g, const Sched& S, const Epi& E, int wv) {
;     const int tid = get_tid_(wv), wid = __builtin_amdgcn_readfirstlane(tid >> 6), lane = tid & 63, wr = wid >> 2, wc = wid & 3, fr = lane & 15, fq = lane >> 4;
;     const int K = g.K, nt = K / BK;
;     unsigned voffA[2], voffB[2];
; #pragma unroll
;     for (int i = 0; i < 2; ++i) { int R, C; stage_rc(tid * 16 + i * 8192, R, C); const int Rb = Epi::PERM ? ((R & ~31) + perm32(R & 31)) : R;
;         voffA[i] = (unsigned)(R * g.lda + C) * 2u; voffB[i] = (unsigned)(Rb * g.ldb + C) * 2u; }
;     const size_t kstep = (size_t)(BK * 2);
;     const size_t hstepA = (size_t)HALF * g.lda * 2, hstepB = (size_t)HALF * g.ldb * 2;
;     const size_t tstepA = 2 * hstepA, tstepB = 2 * hstepB;
;     const unsigned ldsw = (unsigned)wid * 1024u;
;     const int aoff = lds_byte(wr * 64 + fr, fq * 8), boff = lds_byte(wc * 32 + fr, fq * 8);
;     ...
;     Unit cur, nxt; int ui = 0;
;     if (!S.next(0, cur)) return;
;     f32x4 acc[2][2][4][2];
; #pragma unroll
;     for (int a = 0; a < 2; ++a)
; #pragma unroll
;         for (int b = 0; b < 2; ++b)
; #pragma unroll
;             for (int m = 0; m < 4; ++m)
; #pragma unroll
;                 for (int n = 0; n < 2; ++n) acc[a][b][m][n] = (f32x4){0.f, 0.f, 0.f, 0.f};
;     bf16x8 At[4][2], B0[2][2], B1[2][2];
;     const char* cA = (const char*)g.A + (size_t)cur.pm * tstepA + S.a_off(cur); const char* cB = (const char*)g.Bt + (size_t)cur.pn * tstepB;
;     S.a_ready(cur);
;     if constexpr (SP2) {
;         PG8_STAGE(PG8_SB(0, 0), cB, voffB); PG8_STAGE(PG8_SB(0, 1), cB + hstepB, voffB); PG8_STAGE(PG8_SA(0, 0), cA, voffA); PG8_STAGE(PG8_SA(0, 1), cA + hstepA, voffA);
;         if (wr == 1) PG8_BAR;
;         PG8_WAIT_V(2); PG8_BAR;
; template <int PH>
; DI void run_phase(const PP& p, int l, int b, char* lds) {
;     ...
;         pg8::ListOrder S;
;         { const int x = bid & 7, k = bid >> 3;
;           if (k < 12) S = pg8::ListOrder{x, 196 + k, 5, 12, 1};
;           else S = pg8::ListOrder{x, k - 12, (k - 12) < 16 ? 10 : 9, 20, 1}; }
;         pg8::run_list<2>(p, p.h, 1024, p.WTin + (size_t)l * LDP * 1024, 1024, 1024, p.proj, LDP, S_, LDP, lds, S, p.ctrl + 4096 + (b * 2 + l) * 2080);
.LBB0_258:
	s_ashr_i32 s5, s28, 3
	s_cmp_lt_i32 s5, 12
	s_cselect_b64 s[2:3], -1, 0
	s_and_b64 s[0:1], s[2:3], exec
	v_writelane_b32 v255, s94, 29
	s_cselect_b32 s25, 0xc4, -12
	s_add_i32 s25, s25, s5
	s_cmp_lt_i32 s5, 4
	s_cselect_b32 s0, 36, 0
	s_add_i32 s25, s25, s0
	v_writelane_b32 v255, s95, 30
	v_mov_b32_e32 v0, v1
	v_writelane_b32 v255, s90, 31
	s_and_b64 s[0:1], s[90:91], exec
	s_waitcnt vmcnt(63) expcnt(7) lgkmcnt(15)
	s_barrier
	s_cselect_b32 s0, 0x1600000, 0
	v_mbcnt_lo_u32_b32 v0, -1, v0
	s_add_u32 s67, s76, s0
	s_mov_b32 s0, s64
	v_mbcnt_hi_u32_b32 v0, -1, v0
	v_mov_b32_e32 v8, 1
	v_lshl_or_b32 v2, s0, 6, v0
	v_ashrrev_i32_e32 v4, 31, v2
	v_lshrrev_b32_e32 v4, 26, v4
	v_readfirstlane_b32 s4, v2
	v_lshlrev_b32_e32 v3, 4, v2
	v_add_u32_e32 v4, v2, v4
	v_bfe_i32 v2, v2, 27, 1
	v_lshrrev_b32_e32 v2, 22, v2
	v_add_u32_e32 v2, v3, v2
	v_and_b32_e32 v2, 0xfffffc00, v2
	v_sub_u32_e32 v2, v3, v2
	v_ashrrev_i32_e32 v10, 6, v4
	v_lshrrev_b32_e32 v4, 4, v2
	v_bitop3_b32 v2, v4, v2, 32 bitop3:0x6c
	v_ashrrev_i32_e32 v5, 31, v2
	v_lshrrev_b32_e32 v5, 26, v5
	v_add_u32_e32 v5, v2, v5
	v_lshlrev_b32_e32 v4, 3, v10
	v_ashrrev_i32_e32 v11, 6, v5
	v_and_b32_e32 v5, 0xc0, v5
	v_and_b32_e32 v4, -16, v4
	v_sub_u32_e32 v2, v2, v5
	v_add_u32_e32 v4, v11, v4
	v_ashrrev_i16_sdwa v2, v8, sext(v2) dst_sel:DWORD dst_unused:UNUSED_PAD src0_sel:DWORD src1_sel:BYTE_0
	v_lshlrev_b32_e32 v6, 5, v10
	v_bfe_i32 v12, v2, 0, 16
	v_lshlrev_b32_e32 v2, 1, v4
	v_lshrrev_b32_e32 v5, 2, v4
	v_and_b32_e32 v7, 3, v11
	s_mov_b32 s0, 0x1fffe0
	v_and_b32_e32 v6, 32, v6
	v_and_b32_e32 v2, 24, v2
	v_and_b32_e32 v5, 4, v5
	v_and_or_b32 v7, v4, s0, v7
	v_or3_b32 v2, v7, v5, v2
	v_add_lshl_u32 v5, v6, v12, 1
	s_waitcnt vmcnt(0)
	v_lshl_add_u32 v132, v2, 11, v5
	v_add_u32_e32 v2, 0x2000, v3
	v_ashrrev_i32_e32 v3, 31, v2
	v_lshrrev_b32_e32 v3, 22, v3
	v_add_u32_e32 v3, v2, v3
	v_ashrrev_i32_e32 v13, 10, v3
	v_mul_i32_i24_e32 v3, 0x400, v13
	v_sub_u32_e32 v2, v2, v3
	v_lshrrev_b32_e32 v3, 4, v2
	v_bitop3_b32 v2, v3, v2, 32 bitop3:0x6c
	v_lshl_add_u32 v130, v4, 11, v5
	v_ashrrev_i32_e32 v4, 31, v2
	v_lshrrev_b32_e32 v4, 26, v4
	v_lshlrev_b32_e32 v3, 3, v13
	v_add_u32_e32 v4, v2, v4
	s_addc_u32 s75, s77, 0
	v_and_b32_e32 v3, -16, v3
	v_ashrrev_i32_e32 v14, 6, v4
	s_lshl_b32 s1, s28, 3
	s_ashr_i32 s7, s4, 6
	v_add_u32_e32 v3, v14, v3
	v_and_b32_e32 v6, 3, v14
	s_and_b32 s69, s1, 56
	s_and_b32 s1, s25, 7
	v_and_or_b32 v6, v3, s0, v6
	s_ashr_i32 s8, s4, 8
	s_lshl_b32 s79, s7, 10
	s_ashr_i32 s0, s25, 3
	s_or_b32 s73, s1, s69
	s_cmp_lt_i32 s0, 4
	s_cselect_b32 s1, 8, 12
	s_add_i32 s42, s1, s0
	v_and_b32_e32 v4, 0xc0, v4
	s_ashr_i32 s43, s42, 31
	v_sub_u32_e32 v2, v2, v4
	s_lshl_b32 s6, s73, 19
	s_lshl_b64 s[0:1], s[42:43], 19
	v_ashrrev_i16_sdwa v2, v8, sext(v2) dst_sel:DWORD dst_unused:UNUSED_PAD src0_sel:DWORD src1_sel:BYTE_0
	s_add_u32 s14, s67, s0
	v_lshlrev_b32_e32 v5, 5, v13
	v_bfe_i32 v15, v2, 0, 16
	v_lshlrev_b32_e32 v2, 1, v3
	v_lshrrev_b32_e32 v4, 2, v3
	s_addc_u32 s15, s75, s1
	s_add_i32 s43, s79, 0
	v_and_b32_e32 v5, 32, v5
	v_and_b32_e32 v2, 24, v2
	v_and_b32_e32 v4, 4, v4
	s_add_i32 m0, s43, 0x10000
	v_or3_b32 v2, v6, v4, v2
	v_add_lshl_u32 v4, v5, v15, 1
	global_load_lds_dwordx4 v132, s[14:15]
	s_add_i32 m0, s43, 0x12000
	v_lshl_add_u32 v136, v2, 11, v4
	s_add_u32 s0, s14, 0x40000
	global_load_lds_dwordx4 v136, s[14:15]
	s_addc_u32 s1, s15, 0
	s_add_i32 m0, s43, 0x14000
	v_lshl_add_u32 v134, v3, 11, v4
	global_load_lds_dwordx4 v132, s[0:1]
	s_add_i32 m0, s43, 0x16000
	s_add_u32 s12, s84, s6
	s_addc_u32 s13, s85, 0
	s_add_i32 s65, s43, 0x2000
	global_load_lds_dwordx4 v136, s[0:1]
	s_mov_b32 m0, s43
	s_add_u32 s0, s12, 0x40000
	global_load_lds_dwordx4 v130, s[12:13]
	s_mov_b32 m0, s65
	s_addc_u32 s1, s13, 0
	s_add_i32 s24, s43, 0x4000
	global_load_lds_dwordx4 v134, s[12:13]
	s_mov_b32 m0, s24
	s_add_i32 s77, s43, 0x6000
	global_load_lds_dwordx4 v130, s[0:1]
	s_mov_b32 m0, s77
	v_mov_b32_e32 v133, v1
	global_load_lds_dwordx4 v134, s[0:1]
	v_mov_b32_e32 v137, v1
	v_mov_b32_e32 v131, v1
	v_mov_b32_e32 v135, v1
	s_cmp_eq_u32 s8, 1
	v_writelane_b32 v255, s91, 32
	v_lshl_add_u64 v[8:9], s[14:15], 0, v[132:133]
	v_lshl_add_u64 v[6:7], s[14:15], 0, v[136:137]
	v_lshl_add_u64 v[2:3], s[12:13], 0, v[130:131]
	s_cselect_b64 s[0:1], -1, 0
	s_cmp_lg_u32 s8, 1
	v_lshl_add_u64 v[4:5], s[12:13], 0, v[134:135]
	s_cbranch_scc1 .LBB0_260
	s_barrier
; #define PG8_STAGE(bufoff, gbase, voff) do { _Pragma("unroll") for (int _i = 0; _i < 2; ++_i) \
;         __builtin_amdgcn_global_load_lds((const unsigned*)((const char*)(gbase) + (voff)[_i]), (PG8_LAS unsigned*)(lds + (bufoff) + ldsw + _i * 8192), 16, 0, 0); } while (0)
; #define PG8_WAIT_V(n) asm volatile("s_waitcnt vmcnt(" #n ")" ::: "memory")
; #define PG8_BAR __builtin_amdgcn_s_barrier()
; template <class Epi, class Sched, bool ALIGN_EPI = false, bool SP2 = false>
; __device__ __forceinline__ void gemm_phase(PG8_LAS unsigned char* lds, const Gemm g, const Sched& S, const Epi& E, int wv) {
;     ...
;     if constexpr (SP2) {
;         PG8_STAGE(PG8_SB(0, 0), cB, voffB); PG8_STAGE(PG8_SB(0, 1), cB + hstepB, voffB); PG8_STAGE(PG8_SA(0, 0), cA, voffA); PG8_STAGE(PG8_SA(0, 1), cA + hstepA, voffA);
;         if (wr == 1) PG8_BAR;
;         PG8_WAIT_V(2); PG8_BAR;
;         PG8_STAGE(PG8_SB(1, 0), cB + kstep, voffB); PG8_STAGE(PG8_SA(1, 0), cA + kstep, voffA); PG8_STAGE(PG8_SB(1, 1), cB + hstepB + kstep, voffB);
;         PG8_WAIT_V(6); PG8_BAR;
; template <int PH>
; DI void run_phase(const PP& p, int l, int b, char* lds) {
;     ...
;         { const int x = bid & 7, k = bid >> 3;
;           if (k < 12) S = pg8::ListOrder{x, 196 + k, 5, 12, 1};
;           else S = pg8::ListOrder{x, k - 12, (k - 12) < 16 ? 10 : 9, 20, 1}; }
;         pg8::run_list<2>(p, p.h, 1024, p.WTin + (size_t)l * LDP * 1024, 1024, 1024, p.proj, LDP, S_, LDP, lds, S, p.ctrl + 4096 + (b * 2 + l) * 2080);
.LBB0_260:
	s_cmp_lt_u32 s5, 4
	s_cselect_b32 s72, 4, 8
	s_cselect_b32 s96, 6, 4
	s_cmp_lt_u32 s5, 12
	s_cselect_b32 s72, s72, 20
	s_cselect_b32 s96, s96, 10
	v_readlane_b32 s2, v255, 29
	s_lshl_b32 s2, s2, 1
	s_or_b32 s2, s2, s9
	v_readlane_b32 s3, v255, 30
	s_mulk_i32 s2, 0x820
	s_ashr_i32 s3, s2, 31
	s_lshl_b64 s[2:3], s[2:3], 2
	v_readlane_b32 s5, v253, 21
	s_add_u32 s78, s5, s2
	v_readlane_b32 s2, v253, 22
	s_addc_u32 s2, s2, s3
	s_add_i32 m0, s43, 0x18000
	v_writelane_b32 v255, s2, 33
	s_and_b32 s2, s7, 3
	v_lshl_add_u64 v[8:9], v[8:9], 0, s[20:21]
	s_lshl_b32 s5, s8, 13
	s_lshl_b32 s97, s2, 5
	s_lshl_b32 s6, s2, 12
	s_waitcnt vmcnt(2)
	s_barrier
	global_load_lds_dwordx4 v[8:9], off
	v_lshl_add_u64 v[6:7], v[6:7], 0, s[20:21]
	s_add_i32 m0, s43, 0x1a000
	s_add_i32 s30, s43, 0x8000
	s_add_i32 s31, s43, 0xa000
	v_writelane_b32 v255, s2, 34
	global_load_lds_dwordx4 v[6:7], off
	v_lshl_add_u64 v[2:3], v[2:3], 0, s[20:21]
	s_mov_b32 m0, s30
	s_add_u32 s2, s14, 0x40080
	global_load_lds_dwordx4 v[2:3], off
	v_lshl_add_u64 v[2:3], v[4:5], 0, s[20:21]
	s_mov_b32 m0, s31
	s_addc_u32 s3, s15, 0
	global_load_lds_dwordx4 v[2:3], off
	s_add_i32 m0, s43, 0x1c000
	v_lshl_add_u64 v[2:3], s[2:3], 0, v[132:133]
	global_load_lds_dwordx4 v[2:3], off
	v_lshl_add_u64 v[2:3], s[2:3], 0, v[136:137]
	s_add_i32 m0, s43, 0x1e000
	v_bfe_u32 v4, v0, 4, 2
	global_load_lds_dwordx4 v[2:3], off
	v_and_b32_e32 v3, 15, v0
	v_lshlrev_b32_e32 v5, 4, v4
	v_lshlrev_b32_e32 v0, 2, v0
	v_lshlrev_b32_e32 v2, 3, v4
	v_lshl_or_b32 v5, v3, 6, v5
	v_and_b32_e32 v0, 32, v0
	v_bitop3_b32 v6, v5, s5, v0 bitop3:0xde
	v_bitop3_b32 v154, v5, s6, v0 bitop3:0xde
	v_or_b32_e32 v0, s97, v2
	v_lshlrev_b32_e32 v0, 1, v0
	v_lshl_add_u64 v[138:139], s[54:55], 0, v[0:1]
	v_lshl_add_u64 v[140:141], s[56:57], 0, v[0:1]
	v_lshlrev_b32_e32 v0, 14, v10
	v_lshl_or_b32 v147, s8, 6, v3
	v_or_b32_e32 v3, v4, v3
	v_and_b32_e32 v0, 0xffff8000, v0
	v_cmp_eq_u32_e64 s[36:37], 0, v3
	v_lshl_add_u32 v0, v11, 11, v0
	v_and_b32_e32 v3, 1, v10
	v_lshl_or_b32 v0, v3, 6, v0
	v_lshl_add_u32 v142, v12, 1, v0
	v_lshlrev_b32_e32 v0, 14, v13
	v_and_b32_e32 v0, 0xffff8000, v0
	s_waitcnt vmcnt(6)
	v_lshl_add_u32 v0, v14, 11, v0
	v_and_b32_e32 v3, 1, v13
	s_cmpk_lt_u32 s4, 0x100
	v_lshl_or_b32 v0, v3, 6, v0
	s_cselect_b64 s[2:3], -1, 0
	v_or_b32_e32 v155, 16, v147
	v_or_b32_e32 v157, 32, v147
	v_or_b32_e32 v158, 48, v147
	v_add_u32_e32 v159, 0x80, v147
	v_add_u32_e32 v160, 0x90, v147
	v_add_u32_e32 v161, 0xa0, v147
	v_add_u32_e32 v162, 0xb0, v147
	s_mov_b32 s76, 0
	s_add_i32 s74, s96, -1
	v_mov_b32_e32 v143, v1
	v_lshl_add_u32 v144, v15, 1, v0
	v_mov_b32_e32 v145, v1
	v_add_u32_e32 v163, 0, v6
	v_lshlrev_b32_e32 v0, 1, v2
	s_barrier
	s_branch .LBB0_263

; DI int get_tid_(int wv) { int z = 0; asm volatile("" : "+v"(z)); asm volatile("" : "+s"(wv)); const int lane = __builtin_amdgcn_mbcnt_hi(~0u, __builtin_amdgcn_mbcnt_lo(~0u, z)); return (wv << 6) | lane; }
; #define SBAR() __builtin_amdgcn_sched_barrier(0)
; DI int v_st(int k, int c) { const int kk = (k & ~0xC) | ((k & 4) << 1) | ((k & 8) >> 1); return ((kk >> 3) * 4 + (c >> 5)) * 512 + ((kk & 7) * 32 + (c & 31)) * 2; }
; DI int v_rd_base(int lane) { return ((lane & 3) << 3) | (((lane >> 2) & 3) << 6) | (((lane >> 4) & 1) << 5) | (((lane >> 5) & 1) << 8); }
; #define SLOAD_H(Kp, Vp, Cp, k0) do { S.st_v0 = load8(ROW(Vp, k0, sr)); S.st_v1 = load8(ROW(Vp, k0, 32 + sr));              \
;                          S.st_k0 = load8(ROW(Kp, k0, sr)); S.st_k1 = load8(ROW(Kp, k0, 32 + sr)); S.st_c = (Cp)[(k0) + (tid & 63)]; } while (0)
; #define SWRITE_HV(bf) do { *(bf16x8*)(V_lds + (bf) * SHM_V + vst0) = S.st_v0; *(bf16x8*)(V_lds + (bf) * SHM_V + vst0 + vst1_off) = S.st_v1; } while (0)
; DI int block(const PP& p, const ARef& cur, volatile int* slot, unsigned* ctr, int base, int total, char* lds, Seam& S, bool dummy, const unsigned* nrm) {
;     const int tid = get_tid_(p.wv), wid = __builtin_amdgcn_readfirstlane(tid >> 6), lane = tid & 63, r32 = lane & 31, hi = lane >> 5;
;     const int jl = cur.jlo;
;     const int NT = (cur.P0 + QB) / KVBLK - jl;
;     const int qlo = cur.P0 + wid * QBLK, qm = qlo + r32 - 4 * hi;
;     char* V_lds = lds; char* K_lds = lds + 2 * SHM_V;
;     float* ws = (float*)(lds + OFF_WS) + wid * 64; float* li_l = ws, * al_l = ws + 32;
;     float* bias = (float*)(lds + OFF_BIAS);
;     const float* bb = bias + 4 * hi;
;     float m_reg = -1e30f, l_reg = 0; f32x16 o[4] = {};
;     const int sr = tid >> 4, sc = (tid & 15) * 8, vst0 = v_st(sr, sc), kws = KSWZ(sr, sc * 2);
;     constexpr int vst1_off = 8192;
;     const int vb0 = (int)(uintptr_t)V_lds + v_rd_base(lane);
;     const bf16_t* Kh = cur.K; const bf16_t* Vh = cur.V; const float* Ch = cur.cum; const float cref = S.cref;
;     ...
;     f32x16 pA0, pA1, pB0, pB1; float mnA, mnB, alA, alB; bf16x8 pa0, pa1, pa2, pa3;
;     SWRITE_HV(0); SBAR();
;     if (NT > 1) { SLOAD_H(Kh, Vh, Ch, KBASE(1)); }
.LBB0_522:
	v_readlane_b32 s0, v255, 41
	s_nop 1
	v_writelane_b32 v255, s0, 40
	s_cmp_ge_u32 s64, 4
	s_cbranch_scc0 .Lfa_prio_skip
	s_setprio 1
.Lfa_prio_skip:
	v_mov_b32_e32 v0, v1
	s_mov_b32 s0, s64
	v_mbcnt_lo_u32_b32 v0, -1, v0
	v_mbcnt_hi_u32_b32 v220, -1, v0
	v_lshlrev_b32_e32 v0, 3, v220
	v_lshl_or_b32 v222, s0, 6, v220
	v_ashrrev_i32_e32 v199, 4, v222
	v_and_b32_e32 v3, 0xfffff0, v199
	v_lshlrev_b32_e32 v4, 1, v199
	v_and_or_b32 v3, v4, 8, v3
	v_and_b32_e32 v2, 0x78, v0
	v_lshrrev_b32_e32 v3, 1, v3
	v_bfe_u32 v0, v0, 5, 2
	s_add_i32 s0, s6, 0x100
	v_lshrrev_b32_e32 v4, 1, v199
	v_or_b32_e32 v3, v3, v0
	v_and_b32_e32 v0, 3, v199
	s_ashr_i32 s1, s0, 31
	v_and_or_b32 v4, v4, 4, v0
	v_lshlrev_b32_e32 v0, 1, v2
	s_lshr_b32 s1, s1, 26
	v_and_b32_e32 v2, 48, v0
	s_add_i32 s0, s0, s1
	v_lshl_or_b32 v2, v4, 6, v2
	v_readlane_b32 s30, v255, 43
	v_lshl_or_b32 v2, v3, 9, v2
	v_readfirstlane_b32 s15, v222
	v_and_b32_e32 v221, 63, v220
	s_sub_i32 s7, s30, s16
	v_add_u32_e32 v236, 0, v2
	ds_write_b128 v236, v[98:101]
	ds_write_b128 v236, v[102:105] offset:8192
	s_cmp_gt_i32 s7, 1
	s_cselect_b64 s[12:13], -1, 0
	s_lshl_b32 s14, s16, 6
	s_cmp_lt_i32 s7, 2
	s_cbranch_scc1 .LBB0_524
	s_add_i32 s18, s14, 64
	v_add_u32_e32 v6, s18, v199
	v_mov_b64_e32 v[2:3], s[8:9]
	v_mad_i64_i32 v[4:5], s[0:1], v6, s35, v[2:3]
	s_add_i32 s0, s14, 0x60
	s_nop 0
	v_add_u32_e32 v7, s0, v199
	v_mad_i64_i32 v[2:3], s[0:1], v7, s35, v[2:3]
	v_lshl_add_u64 v[4:5], v[4:5], 0, v[0:1]
	v_lshl_add_u64 v[2:3], v[2:3], 0, v[0:1]
	global_load_dwordx4 v[98:101], v[4:5], off
	global_load_dwordx4 v[102:105], v[2:3], off
	v_mov_b64_e32 v[2:3], s[10:11]
	v_mad_i64_i32 v[4:5], s[0:1], v6, s35, v[2:3]
	v_mad_i64_i32 v[2:3], s[0:1], v7, s35, v[2:3]
	v_lshl_add_u64 v[4:5], v[4:5], 0, v[0:1]
	v_lshl_add_u64 v[2:3], v[2:3], 0, v[0:1]
	global_load_dwordx4 v[106:109], v[4:5], off
	global_load_dwordx4 v[110:113], v[2:3], off
	v_or_b32_e32 v2, s18, v221
	v_ashrrev_i32_e32 v3, 31, v2
	v_lshl_add_u64 v[2:3], v[2:3], 2, s[4:5]
	global_load_dword v162, v[2:3], off

; #define SBAR() __builtin_amdgcn_sched_barrier(0)
; #define VMW() asm volatile("s_waitcnt vmcnt(0)" ::: "memory")
; #define SLOAD_H(Kp, Vp, Cp, k0) do { S.st_v0 = load8(ROW(Vp, k0, sr)); S.st_v1 = load8(ROW(Vp, k0, 32 + sr));              \
;                          S.st_k0 = load8(ROW(Kp, k0, sr)); S.st_k1 = load8(ROW(Kp, k0, 32 + sr)); S.st_c = (Cp)[(k0) + (tid & 63)]; } while (0)
; #define SWRITE_HV(bf) do { *(bf16x8*)(V_lds + (bf) * SHM_V + vst0) = S.st_v0; *(bf16x8*)(V_lds + (bf) * SHM_V + vst0 + vst1_off) = S.st_v1; } while (0)
; #define SWRITE_H(bf, cr) do { SWRITE_HV(bf); SWRITE_HK(bf, cr); } while (0)
; #define MASKT(P0_, P1_, t) do { const int kb_ = KBASE(t); if (kb_ + KVBLK - 1 > qlo) mask_tile(P0_, P1_, qm - kb_); } while (0)
; DI void partialSM(f32x16& p0, f32x16& p1, float& m_reg, float& mn, float& alpha) {
;     float pmax = p0[0];
; #pragma unroll
;     for (int r = 1; r < 16; ++r) pmax = fmaxf(pmax, p0[r]);
; #pragma unroll
;     for (int r = 0; r < 16; ++r) pmax = fmaxf(pmax, p1[r]);
;     { auto rr = __builtin_amdgcn_permlane32_swap(__float_as_uint(pmax), __float_as_uint(pmax), false, false);
;       pmax = fmaxf(__uint_as_float(rr[0]), __uint_as_float(rr[1])); }
;     constexpr float C2 = 1.4426950408889634f * SCALE;
;     if (__builtin_expect(__all((pmax - m_reg) * SCALE <= THR), 1)) { mn = m_reg; alpha = 1.f; }
;     else { mn = fmaxf(m_reg, pmax); alpha = __builtin_amdgcn_exp2f((m_reg - mn) * C2); m_reg = mn; }
;     const float mnL = -mn * C2;
; #pragma unroll
;     for (int r = 0; r < 16; ++r) p0[r] = fmaf(p0[r], C2, mnL);
; #pragma unroll
;     for (int r = 0; r < 16; ++r) p1[r] = fmaf(p1[r], C2, mnL);
; #pragma unroll
;     for (int r = 0; r < 16; ++r) p0[r] = __builtin_amdgcn_exp2f(p0[r]);
; }
; DI int block(const PP& p, const ARef& cur, volatile int* slot, unsigned* ctr, int base, int total, char* lds, Seam& S, bool dummy, const unsigned* nrm) {
;     ...
;     f32x16 pA0, pA1, pB0, pB1; float mnA, mnB, alA, alB; bf16x8 pa0, pa1, pa2, pa3;
;     SWRITE_HV(0); SBAR();
;     if (NT > 1) { SLOAD_H(Kh, Vh, Ch, KBASE(1)); }
;     SBAR(); qkt<0>(pA0, pA1, K_lds, r32, hi, S.qr, bb);
;     MASKT(pA0, pA1, 0); partialSM(pA0, pA1, m_reg, mnA, alA);
;     if (NT > 1) { VMW(); SWRITE_H(1, cref); }
;     __syncthreads();
.LBB0_538:
	v_max_f32_e32 v66, v87, v87
	v_max_f32_e32 v67, v86, v86
	v_max_f32_e32 v66, v67, v66
	v_max3_f32 v66, v66, v88, v89
	v_max3_f32 v66, v66, v90, v91
	v_max3_f32 v66, v66, v92, v93
	v_max3_f32 v66, v66, v94, v95
	v_max3_f32 v66, v66, v96, v97
	v_max3_f32 v66, v66, v98, v99
	v_max3_f32 v66, v66, v100, v101
	v_max3_f32 v66, v66, v70, v71
	v_max3_f32 v66, v66, v72, v73
	v_max3_f32 v66, v66, v74, v75
	v_max3_f32 v66, v66, v76, v77
	v_max3_f32 v66, v66, v78, v79
	v_max3_f32 v66, v66, v80, v81
	v_max3_f32 v66, v66, v82, v83
	v_max3_f32 v66, v66, v84, v85
	v_mov_b32_e32 v67, v66
	s_nop 1
	v_permlane32_swap_b32_e32 v66, v67
	v_max_f32_e32 v67, v67, v67
	v_max_f32_e32 v66, v66, v66
	v_max_f32_e32 v66, v66, v67
	v_sub_f32_e32 v67, v66, v178
	v_mul_f32_e32 v67, 0x3db504f3, v67
	v_cmp_ge_f32_e32 vcc, s71, v67
	s_barrier
	s_cmp_eq_u64 vcc, exec
	s_cselect_b64 s[0:1], -1, 0
	v_max_f32_e32 v67, v178, v178
	v_max_f32_e32 v66, v67, v66
	v_sub_f32_e32 v67, v178, v66
	v_mul_f32_e32 v67, 0x3e0293ee, v67
	v_exp_f32_e32 v67, v67
	s_nop 0
	v_cndmask_b32_e64 v241, v67, 1.0, s[0:1]
	v_cmp_gt_f32_e32 vcc, 1.0, v241
	s_cbranch_vccz .LBB0_544
	s_and_saveexec_b64 s[12:13], s[36:37]
	ds_write_b32 v226, v241 offset:128
	s_or_b64 exec, exec, s[12:13]
	s_waitcnt lgkmcnt(0)
	ds_read_b128 v[102:105], v225 offset:224
	ds_read_b128 v[106:109], v225 offset:192
	ds_read_b128 v[110:113], v225 offset:160
	ds_read_b128 v[114:117], v225 offset:128
	s_waitcnt lgkmcnt(3)
	v_pk_mul_f32 v[64:65], v[64:65], v[104:105]
	s_waitcnt lgkmcnt(2)
	v_pk_mul_f32 v[60:61], v[60:61], v[108:109]
	s_waitcnt lgkmcnt(1)
	v_pk_mul_f32 v[56:57], v[56:57], v[112:113]
	s_waitcnt lgkmcnt(0)
	v_pk_mul_f32 v[52:53], v[52:53], v[116:117]
	v_pk_mul_f32 v[62:63], v[62:63], v[102:103]
	v_pk_mul_f32 v[58:59], v[58:59], v[106:107]
	v_pk_mul_f32 v[54:55], v[54:55], v[110:111]
	v_pk_mul_f32 v[50:51], v[50:51], v[114:115]
	v_pk_mul_f32 v[48:49], v[48:49], v[104:105]
	v_pk_mul_f32 v[44:45], v[44:45], v[108:109]
	v_pk_mul_f32 v[40:41], v[40:41], v[112:113]
	v_pk_mul_f32 v[36:37], v[36:37], v[116:117]
	v_pk_mul_f32 v[46:47], v[46:47], v[102:103]
	v_pk_mul_f32 v[42:43], v[42:43], v[106:107]
	v_pk_mul_f32 v[38:39], v[38:39], v[110:111]
	v_pk_mul_f32 v[34:35], v[34:35], v[114:115]
	v_pk_mul_f32 v[32:33], v[32:33], v[104:105]
	v_pk_mul_f32 v[28:29], v[28:29], v[108:109]
	v_pk_mul_f32 v[24:25], v[24:25], v[112:113]
	v_pk_mul_f32 v[20:21], v[20:21], v[116:117]
	v_pk_mul_f32 v[30:31], v[30:31], v[102:103]
	v_pk_mul_f32 v[26:27], v[26:27], v[106:107]
	v_pk_mul_f32 v[22:23], v[22:23], v[110:111]
	v_pk_mul_f32 v[18:19], v[18:19], v[114:115]
	v_pk_mul_f32 v[16:17], v[16:17], v[104:105]
	v_pk_mul_f32 v[12:13], v[12:13], v[108:109]
	v_pk_mul_f32 v[8:9], v[8:9], v[112:113]
	v_pk_mul_f32 v[4:5], v[4:5], v[116:117]
	v_pk_mul_f32 v[14:15], v[14:15], v[102:103]
	v_pk_mul_f32 v[10:11], v[10:11], v[106:107]
	v_pk_mul_f32 v[6:7], v[6:7], v[110:111]
	v_pk_mul_f32 v[2:3], v[2:3], v[114:115]
.LBB0_544:
	v_cndmask_b32_e64 v243, v66, v178, s[0:1]
	v_mul_f32_e32 v178, 0xbe0293ee, v243
	v_fmamk_f32 v66, v86, 0x3e0293ee, v178
	v_fmamk_f32 v67, v87, 0x3e0293ee, v178
	v_fmamk_f32 v68, v88, 0x3e0293ee, v178
	v_fmamk_f32 v69, v89, 0x3e0293ee, v178
	v_fmamk_f32 v102, v90, 0x3e0293ee, v178
	v_fmamk_f32 v103, v91, 0x3e0293ee, v178
	v_fmamk_f32 v104, v92, 0x3e0293ee, v178
	v_fmamk_f32 v105, v93, 0x3e0293ee, v178
	v_fmamk_f32 v106, v94, 0x3e0293ee, v178
	v_fmamk_f32 v107, v95, 0x3e0293ee, v178
	v_fmamk_f32 v108, v96, 0x3e0293ee, v178
	v_fmamk_f32 v109, v97, 0x3e0293ee, v178
	v_fmamk_f32 v98, v98, 0x3e0293ee, v178
	v_fmamk_f32 v99, v99, 0x3e0293ee, v178
	v_fmamk_f32 v100, v100, 0x3e0293ee, v178
	v_fmamk_f32 v101, v101, 0x3e0293ee, v178
	v_fmamk_f32 v86, v70, 0x3e0293ee, v178
	v_fmamk_f32 v95, v71, 0x3e0293ee, v178
	v_fmamk_f32 v96, v72, 0x3e0293ee, v178
	v_fmamk_f32 v97, v73, 0x3e0293ee, v178
	v_fmamk_f32 v179, v74, 0x3e0293ee, v178
	v_fmamk_f32 v87, v75, 0x3e0293ee, v178
	v_fmamk_f32 v88, v76, 0x3e0293ee, v178
	v_fmamk_f32 v89, v77, 0x3e0293ee, v178
	v_fmamk_f32 v90, v78, 0x3e0293ee, v178
	v_fmamk_f32 v91, v79, 0x3e0293ee, v178
	v_fmamk_f32 v92, v80, 0x3e0293ee, v178
	v_fmamk_f32 v93, v81, 0x3e0293ee, v178
	v_exp_f32_e32 v66, v66
	v_exp_f32_e32 v67, v67
	v_exp_f32_e32 v68, v68
	v_exp_f32_e32 v69, v69
	v_exp_f32_e32 v70, v102
	v_exp_f32_e32 v71, v103
	v_exp_f32_e32 v72, v104
	v_exp_f32_e32 v73, v105
	v_exp_f32_e32 v74, v106
	v_exp_f32_e32 v75, v107
	v_exp_f32_e32 v76, v108
	v_exp_f32_e32 v77, v109
	v_exp_f32_e32 v78, v98
	v_exp_f32_e32 v79, v99
	v_exp_f32_e32 v80, v100
	v_exp_f32_e32 v81, v101
	v_fmamk_f32 v94, v82, 0x3e0293ee, v178
	v_fmamk_f32 v180, v83, 0x3e0293ee, v178
	v_fmamk_f32 v181, v84, 0x3e0293ee, v178
	v_fmac_f32_e32 v178, 0x3e0293ee, v85
	s_waitcnt vmcnt(0)
	s_waitcnt vmcnt(4)
	ds_write_b128 v236, v[162:165]
	s_waitcnt vmcnt(3)
	ds_write_b128 v236, v[166:169] offset:8192
	s_waitcnt vmcnt(2)
	ds_write_b128 v224, v[170:173] offset:32768
	s_waitcnt vmcnt(1)
	ds_write_b128 v224, v[174:177] offset:40960
	s_and_saveexec_b64 s[12:13], s[40:41]
	s_cbranch_execz .LBB0_540
	s_waitcnt vmcnt(0)
	v_sub_f32_e32 v114, v219, v242
	v_mul_f32_e32 v114, 0x413504f3, v114
	ds_write_b32 v237, v114
; #define MFMA32(a, b, c) __builtin_amdgcn_mfma_f32_32x32x16_bf16((a), (b), (c), 0, 0, 0)
; DI void finishSM(f32x16& p0, f32x16& p1, float alpha, float& l_reg, bf16x8& pa0, bf16x8& pa1, bf16x8& pa2, bf16x8& pa3) {
; #pragma unroll
;     for (int r = 0; r < 16; ++r) p1[r] = __builtin_amdgcn_exp2f(p1[r]);
;     float ps = 0;
; #pragma unroll
;     for (int r = 0; r < 16; ++r) ps += p0[r];
; #pragma unroll
;     for (int r = 0; r < 16; ++r) ps += p1[r];
;     { auto rr = __builtin_amdgcn_permlane32_swap(__float_as_uint(ps), __float_as_uint(ps), false, false);
;       ps = __uint_as_float(rr[0]) + __uint_as_float(rr[1]); }
;     l_reg = l_reg * alpha + ps;
;     ...
;     PK4(p0, 0, pa0); PK4(p0, 8, pa1); PK4(p1, 0, pa2); PK4(p1, 8, pa3);
;     ...
; }
; template <int KB>
; DI void qkt(f32x16& p0, f32x16& p1, const char* K_lds, int r32, int hi, const bf16x8* qr, const float* bb) {
; #pragma unroll
;     for (int g = 0; g < 4; ++g) {
;         const f32x4 b0 = *(const f32x4*)(bb + KB * 64 + 8 * g), b1 = *(const f32x4*)(bb + KB * 64 + 32 + 8 * g);
; #pragma unroll
;         for (int j = 0; j < 4; ++j) { p0[4 * g + j] = b0[j]; p1[4 * g + j] = b1[j]; }
;     }
;     const char* kb[4];
; #pragma unroll
;     for (int dd = 0; dd < 4; ++dd) kb[dd] = K_lds + KB * SHM_K + KSWZ(r32, (dd * 16 + hi * 8) * 2);
; #pragma unroll
;     for (int d0 = 0; d0 < 8; ++d0) { const char* a = kb[d0 & 3] + (d0 >> 2) * 128;
;         bf16x8 b0 = *reinterpret_cast<const bf16x8*>(a);
;         bf16x8 b1 = *reinterpret_cast<const bf16x8*>(a + 32 * 256);
;         p0 = MFMA32(b0, qr[d0], p0);
;         p1 = MFMA32(b1, qr[d0], p1); }
; }
.LBB0_540:
	s_or_b64 exec, exec, s[12:13]
	s_waitcnt lgkmcnt(0)
	s_barrier
	s_add_i32 s12, s19, -1
	s_cmp_lt_i32 s12, s7
	s_cselect_b64 s[0:1], -1, 0
	s_cmp_ge_i32 s12, s7
	s_cbranch_scc1 .Lfa_c2_skip
	v_add_u32_e32 v194, 0x41, v245
	v_add_u32_e32 v170, 0x41, v244
	v_add_u32_e32 v172, 0x61, v244
	v_ashrrev_i32_e32 v195, 31, v194
	v_mad_i64_i32 v[162:163], s[12:13], v170, s35, v[200:201]
	v_mad_i64_i32 v[166:167], s[12:13], v172, s35, v[200:201]
	v_mad_i64_i32 v[170:171], s[12:13], v170, s35, v[202:203]
	v_mad_i64_i32 v[174:175], s[12:13], v172, s35, v[202:203]
	v_lshl_add_u64 v[194:195], v[194:195], 2, s[4:5]
	global_load_dwordx4 v[162:165], v[162:163], off
	s_nop 0
	global_load_dwordx4 v[166:169], v[166:167], off
	s_nop 0
	global_load_dwordx4 v[170:173], v[170:171], off
	s_nop 0
	global_load_dwordx4 v[174:177], v[174:175], off
	s_nop 0
	global_load_dword v242, v[194:195], off
.Lfa_c2_skip:
	ds_read_b128 v[114:117], v235
	ds_read_b128 v[118:121], v235 offset:32
	ds_read_b128 v[98:101], v235 offset:128
	ds_read_b128 v[102:105], v235 offset:160
	ds_read_b128 v[122:125], v235 offset:64
	ds_read_b128 v[106:109], v235 offset:192
	ds_read_b128 v[126:129], v235 offset:96
	ds_read_b128 v[110:113], v235 offset:224
	ds_read_b128 v[82:85], v233 offset:32768
	ds_read_b128 v[182:185], v233 offset:40960
	v_exp_f32_e32 v87, v87
	v_exp_f32_e32 v88, v88
	v_exp_f32_e32 v89, v89
	s_waitcnt lgkmcnt(1)
	v_mfma_f32_32x32x16_bf16 v[114:129], v[82:85], v[158:161], v[114:129]
	v_exp_f32_e32 v90, v90
	v_exp_f32_e32 v91, v91
	v_exp_f32_e32 v92, v92
	v_exp_f32_e32 v93, v93
	v_exp_f32_e32 v94, v94
	s_waitcnt lgkmcnt(0)
	v_mfma_f32_32x32x16_bf16 v[98:113], v[182:185], v[158:161], v[98:113]
	ds_read_b128 v[82:85], v234 offset:32768
	ds_read_b128 v[182:185], v234 offset:40960
	s_waitcnt lgkmcnt(1)
	v_mfma_f32_32x32x16_bf16 v[114:129], v[82:85], v[154:157], v[114:129]
	s_waitcnt lgkmcnt(0)
	v_mfma_f32_32x32x16_bf16 v[98:113], v[182:185], v[154:157], v[98:113]
	ds_read_b128 v[82:85], v232 offset:32768
	ds_read_b128 v[182:185], v232 offset:40960
	s_waitcnt lgkmcnt(1)
	v_mfma_f32_32x32x16_bf16 v[114:129], v[82:85], v[150:153], v[114:129]
	s_waitcnt lgkmcnt(0)
	v_mfma_f32_32x32x16_bf16 v[98:113], v[182:185], v[150:153], v[98:113]
	ds_read_b128 v[82:85], v231 offset:32768
	ds_read_b128 v[182:185], v231 offset:40960
	s_waitcnt lgkmcnt(1)
	v_mfma_f32_32x32x16_bf16 v[114:129], v[82:85], v[146:149], v[114:129]
	s_waitcnt lgkmcnt(0)
	v_mfma_f32_32x32x16_bf16 v[98:113], v[182:185], v[146:149], v[98:113]
	ds_read_b128 v[82:85], v233 offset:32896
	ds_read_b128 v[182:185], v233 offset:41088
	s_waitcnt lgkmcnt(1)
	v_mfma_f32_32x32x16_bf16 v[114:129], v[82:85], v[142:145], v[114:129]
	s_waitcnt lgkmcnt(0)
	v_mfma_f32_32x32x16_bf16 v[98:113], v[182:185], v[142:145], v[98:113]
	ds_read_b128 v[82:85], v234 offset:32896
	ds_read_b128 v[182:185], v234 offset:41088
	s_waitcnt lgkmcnt(1)
	v_mfma_f32_32x32x16_bf16 v[114:129], v[82:85], v[138:141], v[114:129]
	s_waitcnt lgkmcnt(0)
	v_mfma_f32_32x32x16_bf16 v[98:113], v[182:185], v[138:141], v[98:113]
	ds_read_b128 v[82:85], v232 offset:32896
	ds_read_b128 v[182:185], v232 offset:41088
	s_waitcnt lgkmcnt(1)
	v_mfma_f32_32x32x16_bf16 v[114:129], v[82:85], v[134:137], v[114:129]
	s_waitcnt lgkmcnt(0)
	v_mfma_f32_32x32x16_bf16 v[98:113], v[182:185], v[134:137], v[98:113]
	ds_read_b128 v[82:85], v231 offset:32896
	ds_read_b128 v[182:185], v231 offset:41088
	s_waitcnt lgkmcnt(1)
	v_mfma_f32_32x32x16_bf16 v[114:129], v[82:85], v[130:133], v[114:129]
	v_exp_f32_e32 v85, v97
	v_exp_f32_e32 v97, v178
	v_add_f32_e32 v178, 0, v66
	v_add_f32_e32 v178, v67, v178
	v_add_f32_e32 v178, v68, v178
	v_add_f32_e32 v178, v69, v178
	v_add_f32_e32 v178, v70, v178
	v_add_f32_e32 v178, v71, v178
	v_add_f32_e32 v178, v72, v178
	v_add_f32_e32 v178, v73, v178
	v_add_f32_e32 v178, v74, v178
	v_add_f32_e32 v178, v75, v178
	v_add_f32_e32 v178, v76, v178
	v_add_f32_e32 v178, v77, v178
	v_exp_f32_e32 v82, v86
	v_add_f32_e32 v178, v78, v178
	v_exp_f32_e32 v83, v95
	v_add_f32_e32 v178, v79, v178
	v_exp_f32_e32 v84, v96
	v_add_f32_e32 v178, v80, v178
	v_add_f32_e32 v178, v81, v178
	v_exp_f32_e32 v86, v179
	v_add_f32_e32 v178, v82, v178
	v_add_f32_e32 v178, v83, v178
	v_add_f32_e32 v178, v84, v178
	v_add_f32_e32 v178, v85, v178
	v_add_f32_e32 v178, v86, v178
	v_add_f32_e32 v178, v87, v178
	v_add_f32_e32 v178, v88, v178
	v_add_f32_e32 v178, v89, v178
	v_add_f32_e32 v178, v90, v178
	v_exp_f32_e32 v95, v180
	v_add_f32_e32 v178, v91, v178
	s_waitcnt lgkmcnt(0)
	v_mfma_f32_32x32x16_bf16 v[98:113], v[182:185], v[130:133], v[98:113]
	v_exp_f32_e32 v96, v181
	v_add_f32_e32 v178, v92, v178
	v_add_f32_e32 v178, v93, v178
	v_add_f32_e32 v178, v94, v178
	v_add_f32_e32 v178, v95, v178
	v_add_f32_e32 v178, v96, v178
	v_add_f32_e32 v246, v97, v178
	v_mov_b32_e32 v247, v246
	v_cvt_pk_bf16_f32 v178, v66, v67
	v_cvt_pk_bf16_f32 v179, v68, v69
	v_cvt_pk_bf16_f32 v180, v70, v71
	v_cvt_pk_bf16_f32 v181, v72, v73
	v_cvt_pk_bf16_f32 v182, v74, v75
	v_cvt_pk_bf16_f32 v183, v76, v77
	v_cvt_pk_bf16_f32 v184, v78, v79
	v_cvt_pk_bf16_f32 v185, v80, v81
	v_cvt_pk_bf16_f32 v186, v82, v83
	v_cvt_pk_bf16_f32 v187, v84, v85
	v_cvt_pk_bf16_f32 v188, v86, v87
	v_cvt_pk_bf16_f32 v189, v88, v89
	v_cvt_pk_bf16_f32 v190, v90, v91
	v_cvt_pk_bf16_f32 v191, v92, v93
	v_cvt_pk_bf16_f32 v192, v94, v95
	v_cvt_pk_bf16_f32 v193, v96, v97
	s_nop 1
	v_permlane32_swap_b32_e32 v246, v247
	v_permlane32_swap_b32_e32 v178, v180
	v_permlane32_swap_b32_e32 v179, v181
	v_permlane32_swap_b32_e32 v182, v184
	v_permlane32_swap_b32_e32 v183, v185
	v_permlane32_swap_b32_e32 v186, v188
	v_permlane32_swap_b32_e32 v187, v189
	v_permlane32_swap_b32_e32 v190, v192
	v_permlane32_swap_b32_e32 v191, v193

; DI void phase(const PP& p, unsigned* ctr, int base, int total, char* lds, const unsigned* nrm, bool dummy = false) {
;     ...
;     int L = __builtin_amdgcn_readfirstlane(*slot);
;     __syncthreads();
;     if (L >= total) return;
;     ARef cur = mkref(p, base + L, dummy); Seam S;
;     ...
;     prime(cur, lds, S, p.wv);
;     for (;;) {
;         const int Ln = block(p, cur, slot, ctr, base, total, lds, S, dummy, nrm);
;         if (Ln >= total) break;
;         cur = mkref(p, base + Ln, dummy); cur.jlo = S.jlo_next;
;     }
; }
.LBB0_717:
	s_setprio 0
	v_readlane_b32 s72, v255, 8
	s_movk_i32 s97, 0x3000
	s_mov_b64 s[0:1], 0
	v_readlane_b32 s73, v255, 9
	v_readlane_b32 s74, v255, 10
	v_readlane_b32 s75, v255, 11
	v_readlane_b32 s76, v255, 12
	v_readlane_b32 s77, v255, 13
	v_readlane_b32 s78, v255, 14
	v_readlane_b32 s79, v255, 15
	v_readlane_b32 s80, v255, 16
	v_readlane_b32 s81, v255, 17
	v_readlane_b32 s82, v255, 18
	v_readlane_b32 s83, v255, 19
	v_readlane_b32 s84, v255, 20
	v_readlane_b32 s85, v255, 21
	v_readlane_b32 s86, v255, 22
	v_readlane_b32 s87, v255, 23
